# grid barrier: non-leader workgroups wait on the cross-XCD release word directly (one hop fewer)
# baseline (speedup 1.0000x reference)
; __device__ __forceinline__ unsigned xb_ld(unsigned* p)              { return __hip_atomic_load(p, __ATOMIC_RELAXED, __HIP_MEMORY_SCOPE_AGENT); }
; __device__ __forceinline__ unsigned xb_add(unsigned* p, unsigned v) { return __hip_atomic_fetch_add(p, v, __ATOMIC_RELAXED, __HIP_MEMORY_SCOPE_AGENT); }
; #define XB_SPIN(cond, bar) do { unsigned _sp = 0; while (cond) { __builtin_amdgcn_s_sleep(1); \
;     if ((++_sp & 255u) == 0u) { if (xb_ld(&(bar)[XB_TMO])) break; if (_sp > XB_SPIN_CAP) { atomicAdd(&(bar)[XB_TMO], 1u); break; } } } } while (0)
; __device__ __forceinline__ void xcd_barrier(const XcdBarrier& b) {
;     asm volatile("s_waitcnt vmcnt(0)" ::: "memory");
;     __syncthreads();
;     if (threadIdx.x == 0) {
;         unsigned* bar = b.bar;
;         __builtin_amdgcn_s_waitcnt(0);
;         unsigned nloc = b.st[0], nx = b.st[1];
;         if (nloc == 0u) { xcd_barrier_complete(bar, b.x, nloc, nx); b.st[0] = nloc; b.st[1] = nx; }
;         const unsigned old = xb_add(&bar[XB_XSUB(b.x)], 1u);
;         const unsigned gen = old / nloc;
;         if (old + 1u == (gen + 1u) * nloc) {
;             __builtin_amdgcn_fence(__ATOMIC_RELEASE, "agent");
;             asm volatile("s_waitcnt vmcnt(0)" ::: "memory");
;             const unsigned og = xb_add(&bar[XB_TOP], 1u);
;             const unsigned tg = og / nx;
;             if (og + 1u == (tg + 1u) * nx) xb_add(&bar[XB_TOPGEN], 1u);
;             else XB_SPIN(xb_ld(&bar[XB_TOPGEN]) == tg, bar);
;             __builtin_amdgcn_fence(__ATOMIC_ACQUIRE, "agent");
;             xb_add(&bar[XB_XGEN(b.x)], 1u);
;             asm volatile("s_waitcnt vmcnt(0)" ::: "memory");
;         } else {
;             XB_SPIN(xb_ld(&bar[XB_XGEN(b.x)]) == gen, bar);
;             __builtin_amdgcn_fence(__ATOMIC_ACQUIRE, "agent");
;             asm volatile("s_waitcnt vmcnt(0)" ::: "memory");
;         }
;     }
;     __syncthreads();
; }
.LBB0_196:
	s_or_b64 exec, exec, s[8:9]
	v_cvt_f32_u32_e32 v4, v2
	s_waitcnt vmcnt(0)
	v_readfirstlane_b32 s8, v3
	v_sub_u32_e32 v3, 0, v2
	v_rcp_iflag_f32_e32 v4, v4
	v_add_u32_e32 v5, s8, v1
	v_mul_f32_e32 v4, 0x4f7ffffe, v4
	v_cvt_u32_f32_e32 v4, v4
	v_mul_lo_u32 v1, v3, v4
	v_mul_hi_u32 v1, v4, v1
	v_add_u32_e32 v1, v4, v1
	v_mul_hi_u32 v1, v5, v1
	v_mul_lo_u32 v3, v1, v2
	v_sub_u32_e32 v3, v5, v3
	v_add_u32_e32 v4, 1, v1
	v_cmp_ge_u32_e32 vcc, v3, v2
	s_nop 1
	v_cndmask_b32_e32 v1, v1, v4, vcc
	v_sub_u32_e32 v4, v3, v2
	v_cndmask_b32_e32 v3, v3, v4, vcc
	v_add_u32_e32 v4, 1, v1
	v_cmp_ge_u32_e32 vcc, v3, v2
	v_add_u32_e32 v3, 1, v5
	s_nop 0
	v_cndmask_b32_e32 v1, v1, v4, vcc
	v_mul_lo_u32 v4, v2, v1
	v_add_u32_e32 v2, v4, v2
	v_cmp_ne_u32_e32 vcc, v3, v2
	s_and_saveexec_b64 s[8:9], vcc
	s_xor_b64 s[8:9], exec, s[8:9]
	s_cbranch_execz .LBB0_210
	v_readlane_b32 s22, v251, 49
	v_readlane_b32 s23, v251, 50
	s_waitcnt lgkmcnt(0)
	s_nop 3
	global_load_dword v0, v16, s[22:23] sc1
	s_waitcnt vmcnt(0)
	v_cmp_eq_u32_e32 vcc, v0, v1
	s_and_saveexec_b64 s[22:23], vcc
	s_cbranch_execz .LBB0_209
	s_mov_b32 s21, 1
	s_mov_b64 s[36:37], 0
	s_branch .LBB0_200

; __device__ __forceinline__ unsigned xb_ld(unsigned* p)              { return __hip_atomic_load(p, __ATOMIC_RELAXED, __HIP_MEMORY_SCOPE_AGENT); }
; __device__ __forceinline__ unsigned xb_add(unsigned* p, unsigned v) { return __hip_atomic_fetch_add(p, v, __ATOMIC_RELAXED, __HIP_MEMORY_SCOPE_AGENT); }
; #define XB_SPIN(cond, bar) do { unsigned _sp = 0; while (cond) { __builtin_amdgcn_s_sleep(1); \
;     if ((++_sp & 255u) == 0u) { if (xb_ld(&(bar)[XB_TMO])) break; if (_sp > XB_SPIN_CAP) { atomicAdd(&(bar)[XB_TMO], 1u); break; } } } } while (0)
; __device__ __forceinline__ void xcd_barrier(const XcdBarrier& b) {
;     ...
;             else XB_SPIN(xb_ld(&bar[XB_TOPGEN]) == tg, bar);
;             __builtin_amdgcn_fence(__ATOMIC_ACQUIRE, "agent");
;             xb_add(&bar[XB_XGEN(b.x)], 1u);
;             asm volatile("s_waitcnt vmcnt(0)" ::: "memory");
;         } else {
;             XB_SPIN(xb_ld(&bar[XB_XGEN(b.x)]) == gen, bar);
.LBB0_202:
	v_readlane_b32 s34, v251, 49
	v_readlane_b32 s35, v251, 50
	s_add_i32 s21, s21, 1
	s_mov_b64 s[42:43], -1
	s_nop 2
	global_load_dword v0, v16, s[34:35] sc1
	s_waitcnt vmcnt(0)
	v_cmp_ne_u32_e32 vcc, v0, v1
	s_orn2_b64 s[40:41], vcc, exec
	s_branch .LBB0_199

; __device__ __forceinline__ unsigned xb_ld(unsigned* p)              { return __hip_atomic_load(p, __ATOMIC_RELAXED, __HIP_MEMORY_SCOPE_AGENT); }
; __device__ __forceinline__ unsigned xb_add(unsigned* p, unsigned v) { return __hip_atomic_fetch_add(p, v, __ATOMIC_RELAXED, __HIP_MEMORY_SCOPE_AGENT); }
; #define XB_SPIN(cond, bar) do { unsigned _sp = 0; while (cond) { __builtin_amdgcn_s_sleep(1); \
;     if ((++_sp & 255u) == 0u) { if (xb_ld(&(bar)[XB_TMO])) break; if (_sp > XB_SPIN_CAP) { atomicAdd(&(bar)[XB_TMO], 1u); break; } } } } while (0)
; __device__ __forceinline__ void xcd_barrier(const XcdBarrier& b) {
;     ...
;             else XB_SPIN(xb_ld(&bar[XB_TOPGEN]) == tg, bar);
;             __builtin_amdgcn_fence(__ATOMIC_ACQUIRE, "agent");
;             xb_add(&bar[XB_XGEN(b.x)], 1u);
;             asm volatile("s_waitcnt vmcnt(0)" ::: "memory");
;         } else {
;             XB_SPIN(xb_ld(&bar[XB_XGEN(b.x)]) == gen, bar);
.LBB0_869:
	v_readlane_b32 s34, v251, 49
	v_readlane_b32 s35, v251, 50
	s_add_i32 s21, s21, 1
	s_mov_b64 s[44:45], -1
	s_nop 2
	global_load_dword v0, v16, s[34:35] sc1
	s_waitcnt vmcnt(0)
	v_cmp_ne_u32_e32 vcc, v0, v1
	s_orn2_b64 s[42:43], vcc, exec
	s_branch .LBB0_866

; __device__ __forceinline__ unsigned xb_ld(unsigned* p)              { return __hip_atomic_load(p, __ATOMIC_RELAXED, __HIP_MEMORY_SCOPE_AGENT); }
; __device__ __forceinline__ unsigned xb_add(unsigned* p, unsigned v) { return __hip_atomic_fetch_add(p, v, __ATOMIC_RELAXED, __HIP_MEMORY_SCOPE_AGENT); }
; #define XB_SPIN(cond, bar) do { unsigned _sp = 0; while (cond) { __builtin_amdgcn_s_sleep(1); \
;     if ((++_sp & 255u) == 0u) { if (xb_ld(&(bar)[XB_TMO])) break; if (_sp > XB_SPIN_CAP) { atomicAdd(&(bar)[XB_TMO], 1u); break; } } } } while (0)
; __device__ __forceinline__ void xcd_barrier(const XcdBarrier& b) {
;     asm volatile("s_waitcnt vmcnt(0)" ::: "memory");
;     __syncthreads();
;     if (threadIdx.x == 0) {
;         unsigned* bar = b.bar;
;         __builtin_amdgcn_s_waitcnt(0);
;         unsigned nloc = b.st[0], nx = b.st[1];
;         if (nloc == 0u) { xcd_barrier_complete(bar, b.x, nloc, nx); b.st[0] = nloc; b.st[1] = nx; }
;         const unsigned old = xb_add(&bar[XB_XSUB(b.x)], 1u);
;         const unsigned gen = old / nloc;
;         if (old + 1u == (gen + 1u) * nloc) {
;             __builtin_amdgcn_fence(__ATOMIC_RELEASE, "agent");
;             asm volatile("s_waitcnt vmcnt(0)" ::: "memory");
;             const unsigned og = xb_add(&bar[XB_TOP], 1u);
;             const unsigned tg = og / nx;
;             if (og + 1u == (tg + 1u) * nx) xb_add(&bar[XB_TOPGEN], 1u);
;             else XB_SPIN(xb_ld(&bar[XB_TOPGEN]) == tg, bar);
;             __builtin_amdgcn_fence(__ATOMIC_ACQUIRE, "agent");
;             xb_add(&bar[XB_XGEN(b.x)], 1u);
;             asm volatile("s_waitcnt vmcnt(0)" ::: "memory");
;         } else {
;             XB_SPIN(xb_ld(&bar[XB_XGEN(b.x)]) == gen, bar);
;             __builtin_amdgcn_fence(__ATOMIC_ACQUIRE, "agent");
;             asm volatile("s_waitcnt vmcnt(0)" ::: "memory");
;         }
;     }
;     __syncthreads();
; }
.LBB0_1263:
	s_or_b64 exec, exec, s[8:9]
	v_cvt_f32_u32_e32 v4, v2
	s_waitcnt vmcnt(0)
	v_readfirstlane_b32 s4, v3
	v_sub_u32_e32 v3, 0, v2
	v_rcp_iflag_f32_e32 v4, v4
	v_add_u32_e32 v5, s4, v1
	v_mul_f32_e32 v4, 0x4f7ffffe, v4
	v_cvt_u32_f32_e32 v4, v4
	v_mul_lo_u32 v1, v3, v4
	v_mul_hi_u32 v1, v4, v1
	v_add_u32_e32 v1, v4, v1
	v_mul_hi_u32 v1, v5, v1
	v_mul_lo_u32 v3, v1, v2
	v_sub_u32_e32 v3, v5, v3
	v_add_u32_e32 v4, 1, v1
	v_cmp_ge_u32_e32 vcc, v3, v2
	s_nop 1
	v_cndmask_b32_e32 v1, v1, v4, vcc
	v_sub_u32_e32 v4, v3, v2
	v_cndmask_b32_e32 v3, v3, v4, vcc
	v_add_u32_e32 v4, 1, v1
	v_cmp_ge_u32_e32 vcc, v3, v2
	v_add_u32_e32 v3, 1, v5
	s_nop 0
	v_cndmask_b32_e32 v1, v1, v4, vcc
	v_mul_lo_u32 v4, v2, v1
	v_add_u32_e32 v2, v4, v2
	v_cmp_ne_u32_e32 vcc, v3, v2
	s_and_saveexec_b64 s[8:9], vcc
	s_xor_b64 s[8:9], exec, s[8:9]
	s_cbranch_execz .LBB0_1277
	v_readlane_b32 s22, v251, 49
	v_readlane_b32 s23, v251, 50
	s_waitcnt lgkmcnt(0)
	s_nop 3
	global_load_dword v0, v16, s[22:23] sc1
	s_waitcnt vmcnt(0)
	v_cmp_eq_u32_e32 vcc, v0, v1
	s_and_saveexec_b64 s[22:23], vcc
	s_cbranch_execz .LBB0_1276
	s_mov_b32 s4, 1
	s_mov_b64 s[36:37], 0
	s_branch .LBB0_1267

; __device__ __forceinline__ unsigned xb_ld(unsigned* p)              { return __hip_atomic_load(p, __ATOMIC_RELAXED, __HIP_MEMORY_SCOPE_AGENT); }
; #define XB_SPIN(cond, bar) do { unsigned _sp = 0; while (cond) { __builtin_amdgcn_s_sleep(1); \
;     if ((++_sp & 255u) == 0u) { if (xb_ld(&(bar)[XB_TMO])) break; if (_sp > XB_SPIN_CAP) { atomicAdd(&(bar)[XB_TMO], 1u); break; } } } } while (0)
; __device__ __forceinline__ void xcd_barrier(const XcdBarrier& b) {
;     ...
;             XB_SPIN(xb_ld(&bar[XB_XGEN(b.x)]) == gen, bar);
.LBB0_1269:
	v_readlane_b32 s34, v251, 49
	v_readlane_b32 s35, v251, 50
	s_add_i32 s4, s4, 1
	s_mov_b64 s[42:43], -1
	s_nop 2
	global_load_dword v0, v16, s[34:35] sc1
	s_waitcnt vmcnt(0)
	v_cmp_ne_u32_e32 vcc, v0, v1
	s_orn2_b64 s[40:41], vcc, exec
	s_branch .LBB0_1266
